# B5 + de-serialised strip epilogues (FFN-down and out-proj): all 8 tail loads issued up front with counted waits, main stats atomic deferred (FFN-down)
# speedup vs baseline: 1.0098x; 1.0059x over previous
; #define GAS __attribute__((address_space(1)))
; __device__ __forceinline__ float h16_lo(unsigned u) { return (float)__builtin_bit_cast(h16x2, u).x; }
; __device__ __forceinline__ float h16_hi(unsigned u) { return (float)__builtin_bit_cast(h16x2, u).y; }
;     __device__ __forceinline__ void operator()(const f32x4 (&acc)[2][2][4][2], const Unit& u, int wr, int wc, int fr, int fq, const PG8_LAS float*) const {
;     ...
;                 atomic_add_f32((gf32*)((GAS char*)(stats + u.pm * BM + ai * HALF) + so), v); }
;     __device__ __forceinline__ void strip(const f32x4 (&accS)[2], const Unit& u, int wr, int wc, int fr, int fq) const {
;         const GAS char* gate = (const GAS char*)(ada_l + (size_t)(2 * 6 + chunk) * DM + u.pn * BM);
;         const GAS char* lsp = (const GAS char*)(ls + u.pn * BM);
;         const GAS char* gnp = (const GAS char*)(gnext + u.pn * BM);
;         const GAS char* scp = (const GAS char*)(ada_n + (size_t)(2 * 6 + sc_chunk) * DM + u.pn * BM);
;         const GAS char* bt = (const GAS char*)(base + (size_t)u.srow * DM + u.pn * BM);
;         GAS char* ot = (GAS char*)(out + (size_t)u.srow * DM + u.pn * BM);
;         GAS char* at = (GAS char*)(An + (size_t)u.srow * DM + u.pn * BM);
;         asm volatile("" : "+v"(fr), "+v"(fq));
;         const unsigned co = (unsigned)(wc * 32 + 8 * fq + 4 * wr) * 4u, lo = (unsigned)(fr * DM) * 2u + (co >> 1), so = (unsigned)fr * 4u;
;         float q = 0.f;
; #pragma unroll
;         for (int bj = 0; bj < 2; ++bj) { const unsigned c = co + (unsigned)(bj * HALF) * 4u, o = lo + (unsigned)(bj * HALF) * 2u;
;             f32x4 gv = *(const gf32x4*)(gate + c); if (ls) gv = gv * *(const gf32x4*)(lsp + c);
;             const u32x2 b = *(const gu32x2*)(bt + o);
;             const f32x4 x0 = (f32x4){h16_lo(b.x), h16_hi(b.x), h16_lo(b.y), h16_hi(b.y)} + accS[bj] * gv; { u32x2 w; w.x = pk_h16(x0.x, x0.y); w.y = pk_h16(x0.z, x0.w); *(gu32x2*)(ot + o) = w; }
;             q += (x0.x * x0.x + x0.y * x0.y) + (x0.z * x0.z + x0.w * x0.w);
;             if (An) { const f32x4 y0 = x0 * (*(const gf32x4*)(gnp + c) * (*(const gf32x4*)(scp + c) + 1.0f));
;                 u32x2 w; w.x = cvt_pk_bf16(y0.x, y0.y); w.y = cvt_pk_bf16(y0.z, y0.w); *(gu32x2*)(at + o) = w; } }
;         if (stats) { q += __shfl_xor(q, 16); q += __shfl_xor(q, 32); if (fq == 0) atomic_add_f32((gf32*)((GAS char*)(stats + u.srow) + so), q); }
.LBB0_1341:
	s_or_b64 exec, exec, s[28:29]
	s_add_u32 s38, s87, s52
	s_addc_u32 s39, s88, s53
	s_add_u32 s4, s89, s52
	s_addc_u32 s5, s90, s53
	s_ashr_i32 s1, s0, 31
	s_waitcnt lgkmcnt(1)
	v_add_f32_e32 v10, v12, v13
	s_lshl_b64 s[20:21], s[0:1], 12
	global_atomic_add_f32 v[8:9], v10, off offset:512
	s_add_u32 s11, s68, s20
	v_mov_b32_e32 v9, v231
	v_mov_b32_e32 v8, v232
	s_addc_u32 s22, s69, s21
	s_add_u32 s28, s11, s14
	v_lshl_add_u32 v20, v9, 5, s84
	v_lshrrev_b32_e32 v10, 1, v20
	s_addc_u32 s29, s22, s15
	v_lshl_add_u32 v21, v8, 12, v10
	s_waitcnt lgkmcnt(0)
	global_load_dwordx2 v[24:25], v21, s[28:29]
	global_load_dwordx4 v[26:29], v20, s[38:39]
	global_load_dwordx4 v[44:47], v20, s[4:5]
	global_load_dwordx4 v[48:51], v20, s[12:13]
	global_load_dwordx2 v[30:31], v21, s[28:29] offset:256
	global_load_dwordx4 v[32:35], v20, s[38:39] offset:512
	global_load_dwordx4 v[52:55], v20, s[4:5] offset:512
	global_load_dwordx4 v[56:59], v20, s[12:13] offset:512
	s_add_u32 s11, s72, s20
	s_addc_u32 s20, s73, s21
	s_add_u32 s14, s11, s14
	s_addc_u32 s15, s20, s15
	v_cmp_eq_u32_e32 vcc, 0, v9
	s_waitcnt vmcnt(4)
	v_cvt_f32_f16_e32 v16, v24
	v_cvt_f32_f16_e32 v18, v25
	v_cvt_f32_f16_sdwa v19, v25 dst_sel:DWORD dst_unused:UNUSED_PAD src0_sel:WORD_1
	v_cvt_f32_f16_sdwa v17, v24 dst_sel:DWORD dst_unused:UNUSED_PAD src0_sel:WORD_1
	s_nop 0
	v_pk_fma_f32 v[14:15], v[6:7], v[28:29], v[18:19]
	v_pk_fma_f32 v[16:17], v[4:5], v[26:27], v[16:17]
	v_cvt_pk_f16_f32 v5, v14, v15
	v_cvt_pk_f16_f32 v4, v16, v17
	global_store_dwordx2 v21, v[4:5], s[28:29]
	v_pk_add_f32 v[44:45], v[44:45], 1.0 op_sel_hi:[1,0]
	v_pk_add_f32 v[46:47], v[46:47], 1.0 op_sel_hi:[1,0]
	v_pk_mul_f32 v[44:45], v[48:49], v[44:45]
	v_pk_mul_f32 v[46:47], v[50:51], v[46:47]
	v_pk_mul_f32 v[44:45], v[44:45], v[16:17]
	v_pk_mul_f32 v[46:47], v[46:47], v[14:15]
	v_cvt_pk_bf16_f32 v44, v44, v45
	s_nop 0
	v_cvt_pk_bf16_f32 v45, v46, v47
	s_nop 0
	global_store_dwordx2 v21, v[44:45], s[14:15]
	s_waitcnt vmcnt(2)
	v_cvt_f32_f16_e32 v12, v30
	v_cvt_f32_f16_e32 v18, v31
	v_cvt_f32_f16_sdwa v19, v31 dst_sel:DWORD dst_unused:UNUSED_PAD src0_sel:WORD_1
	v_cvt_f32_f16_sdwa v13, v30 dst_sel:DWORD dst_unused:UNUSED_PAD src0_sel:WORD_1
	s_nop 0
	v_pk_fma_f32 v[6:7], v[2:3], v[34:35], v[18:19]
	v_pk_fma_f32 v[18:19], v[0:1], v[32:33], v[12:13]
	v_cvt_pk_f16_f32 v1, v6, v7
	v_cvt_pk_f16_f32 v0, v18, v19
	global_store_dwordx2 v21, v[0:1], s[28:29] offset:256
	v_mul_f32_e32 v0, v17, v17
	v_mul_f32_e32 v1, v15, v15
	v_fmac_f32_e32 v0, v16, v16
	v_fmac_f32_e32 v1, v14, v14
	v_add_f32_e32 v0, v0, v1
	v_mul_f32_e32 v1, v19, v19
	v_mul_f32_e32 v14, v7, v7
	v_fmac_f32_e32 v1, v18, v18
	v_fmac_f32_e32 v14, v6, v6
	v_add_f32_e32 v1, v1, v14
	v_add_f32_e32 v0, v0, v1
	ds_bpermute_b32 v1, v40, v0
	s_waitcnt lgkmcnt(0)
	v_add_f32_e32 v0, v0, v1
	ds_bpermute_b32 v1, v41, v0
	v_pk_add_f32 v[52:53], v[52:53], 1.0 op_sel_hi:[1,0]
	v_pk_add_f32 v[54:55], v[54:55], 1.0 op_sel_hi:[1,0]
	v_pk_mul_f32 v[2:3], v[56:57], v[52:53]
	v_pk_mul_f32 v[4:5], v[58:59], v[54:55]
	v_pk_mul_f32 v[2:3], v[2:3], v[18:19]
	v_pk_mul_f32 v[4:5], v[4:5], v[6:7]
	v_cvt_pk_bf16_f32 v2, v2, v3
	s_nop 0
	v_cvt_pk_bf16_f32 v3, v4, v5
	s_nop 0
	global_store_dwordx2 v21, v[2:3], s[14:15] offset:256
	s_and_saveexec_b64 s[4:5], vcc
	s_cbranch_execz .LBB0_1343
	s_lshl_b64 s[0:1], s[0:1], 2
	v_readlane_b32 s11, v254, 50
	s_add_u32 s0, s11, s0
	v_readlane_b32 s11, v254, 52
	s_addc_u32 s1, s11, s1
	v_lshlrev_b32_e32 v2, 2, v8
	s_waitcnt lgkmcnt(0)
	v_add_f32_e32 v0, v0, v1
	global_atomic_add_f32 v2, v0, s[0:1]

; #define GAS __attribute__((address_space(1)))
; __device__ __forceinline__ float h16_lo(unsigned u) { return (float)__builtin_bit_cast(h16x2, u).x; }
; __device__ __forceinline__ float h16_hi(unsigned u) { return (float)__builtin_bit_cast(h16x2, u).y; }
;     __device__ __forceinline__ void operator()(const f32x4 (&acc)[2][2][4][2], const Unit& u, int wr, int wc, int fr, int fq, const PG8_LAS float*) const {
;     ...
;                 atomic_add_f32((gf32*)((GAS char*)(stats + u.pm * BM + ai * HALF) + so), v); }
;     __device__ __forceinline__ void strip(const f32x4 (&accS)[2], const Unit& u, int wr, int wc, int fr, int fq) const {
;         const GAS char* gate = (const GAS char*)(ada_l + (size_t)(2 * 6 + chunk) * DM + u.pn * BM);
;         const GAS char* lsp = (const GAS char*)(ls + u.pn * BM);
;         const GAS char* gnp = (const GAS char*)(gnext + u.pn * BM);
;         const GAS char* scp = (const GAS char*)(ada_n + (size_t)(2 * 6 + sc_chunk) * DM + u.pn * BM);
;         const GAS char* bt = (const GAS char*)(base + (size_t)u.srow * DM + u.pn * BM);
;         GAS char* ot = (GAS char*)(out + (size_t)u.srow * DM + u.pn * BM);
;         GAS char* at = (GAS char*)(An + (size_t)u.srow * DM + u.pn * BM);
;         asm volatile("" : "+v"(fr), "+v"(fq));
;         const unsigned co = (unsigned)(wc * 32 + 8 * fq + 4 * wr) * 4u, lo = (unsigned)(fr * DM) * 2u + (co >> 1), so = (unsigned)fr * 4u;
;         float q = 0.f;
; #pragma unroll
;         for (int bj = 0; bj < 2; ++bj) { const unsigned c = co + (unsigned)(bj * HALF) * 4u, o = lo + (unsigned)(bj * HALF) * 2u;
;             f32x4 gv = *(const gf32x4*)(gate + c); if (ls) gv = gv * *(const gf32x4*)(lsp + c);
;             const u32x2 b = *(const gu32x2*)(bt + o);
;             const f32x4 x0 = (f32x4){h16_lo(b.x), h16_hi(b.x), h16_lo(b.y), h16_hi(b.y)} + accS[bj] * gv; { u32x2 w; w.x = pk_h16(x0.x, x0.y); w.y = pk_h16(x0.z, x0.w); *(gu32x2*)(ot + o) = w; }
;             q += (x0.x * x0.x + x0.y * x0.y) + (x0.z * x0.z + x0.w * x0.w);
;             if (An) { const f32x4 y0 = x0 * (*(const gf32x4*)(gnp + c) * (*(const gf32x4*)(scp + c) + 1.0f));
;                 u32x2 w; w.x = cvt_pk_bf16(y0.x, y0.y); w.y = cvt_pk_bf16(y0.z, y0.w); *(gu32x2*)(at + o) = w; } }
;         if (stats) { q += __shfl_xor(q, 16); q += __shfl_xor(q, 32); if (fq == 0) atomic_add_f32((gf32*)((GAS char*)(stats + u.srow) + so), q); }
.LBB0_1639:
	s_or_b64 exec, exec, s[54:55]
	s_add_u32 s56, s94, s14
	s_addc_u32 s57, s95, s15
	s_add_u32 s8, s96, s14
	s_addc_u32 s9, s97, s15
	s_ashr_i32 s3, s2, 31
	s_waitcnt lgkmcnt(1)
	v_add_f32_e32 v10, v12, v13
	s_lshl_b64 s[14:15], s[2:3], 12
	s_add_u32 s20, s72, s14
	v_mov_b32_e32 v63, v231
	v_mov_b32_e32 v62, v232
	s_addc_u32 s21, s73, s15
	s_add_u32 s54, s20, s52
	v_lshl_add_u32 v160, v63, 5, s91
	v_lshrrev_b32_e32 v60, 1, v160
	s_addc_u32 s55, s21, s53
	v_lshl_add_u32 v60, v62, 12, v60
	s_add_u32 s14, s76, s14
	s_addc_u32 s15, s75, s15
	s_add_u32 s14, s14, s52
	s_addc_u32 s15, s15, s53
	s_waitcnt lgkmcnt(0)
	s_and_b64 vcc, exec, s[40:41]
	s_cbranch_vccnz .Lst_fd_ld
	global_load_dwordx4 v[44:47], v160, s[8:9]
	global_load_dwordx4 v[48:51], v160, s[12:13]
	global_load_dwordx4 v[52:55], v160, s[8:9] offset:512
	global_load_dwordx4 v[56:59], v160, s[12:13] offset:512
.Lst_fd_ld:
	global_load_dwordx2 v[22:23], v60, s[54:55]
	global_load_dwordx4 v[24:27], v160, s[56:57]
	global_load_dwordx2 v[28:29], v60, s[54:55] offset:256
	global_load_dwordx4 v[30:33], v160, s[56:57] offset:512
	global_atomic_add_f32 v[8:9], v10, off offset:512
	s_waitcnt vmcnt(3)
	v_cvt_f32_f16_e32 v18, v22
	v_cvt_f32_f16_e32 v20, v23
	v_cvt_f32_f16_sdwa v21, v23 dst_sel:DWORD dst_unused:UNUSED_PAD src0_sel:WORD_1
	v_cvt_f32_f16_sdwa v19, v22 dst_sel:DWORD dst_unused:UNUSED_PAD src0_sel:WORD_1
	s_nop 0
	v_pk_fma_f32 v[6:7], v[6:7], v[26:27], v[20:21]
	v_pk_fma_f32 v[4:5], v[4:5], v[24:25], v[18:19]
	v_cvt_pk_f16_f32 v13, v6, v7
	v_cvt_pk_f16_f32 v12, v4, v5
	global_store_dwordx2 v60, v[12:13], s[54:55]
	s_and_b64 vcc, exec, s[40:41]
	s_cbranch_vccnz .Lst_fd_c1_noan
	v_pk_add_f32 v[46:47], v[46:47], 1.0 op_sel_hi:[1,0]
	v_pk_add_f32 v[44:45], v[44:45], 1.0 op_sel_hi:[1,0]
	v_pk_mul_f32 v[16:17], v[50:51], v[46:47]
	v_pk_mul_f32 v[14:15], v[48:49], v[44:45]
	v_pk_mul_f32 v[16:17], v[6:7], v[16:17]
	v_pk_mul_f32 v[14:15], v[4:5], v[14:15]
	s_nop 0
	v_cvt_pk_bf16_f32 v14, v14, v15
	v_cvt_pk_bf16_f32 v15, v16, v17
	s_nop 0
	global_store_dwordx2 v60, v[14:15], s[14:15]
	s_waitcnt vmcnt(3)
	s_branch .Lst_fd_c1
.Lst_fd_c1_noan:
	s_waitcnt vmcnt(2)
.Lst_fd_c1:
	v_cvt_f32_f16_e32 v18, v28
	v_cvt_f32_f16_e32 v20, v29
	v_cvt_f32_f16_sdwa v21, v29 dst_sel:DWORD dst_unused:UNUSED_PAD src0_sel:WORD_1
	v_cvt_f32_f16_sdwa v19, v28 dst_sel:DWORD dst_unused:UNUSED_PAD src0_sel:WORD_1
	s_nop 0
	v_pk_fma_f32 v[2:3], v[2:3], v[32:33], v[20:21]
	v_pk_fma_f32 v[0:1], v[0:1], v[30:31], v[18:19]
	v_cvt_pk_f16_f32 v13, v2, v3
	v_cvt_pk_f16_f32 v12, v0, v1
	global_store_dwordx2 v60, v[12:13], s[54:55] offset:256
	s_and_b64 vcc, exec, s[40:41]
	s_cbranch_vccnz .LBB0_1643
	v_pk_add_f32 v[52:53], v[52:53], 1.0 op_sel_hi:[1,0]
	v_pk_add_f32 v[54:55], v[54:55], 1.0 op_sel_hi:[1,0]
	v_pk_mul_f32 v[14:15], v[56:57], v[52:53]
	v_pk_mul_f32 v[16:17], v[58:59], v[54:55]
	v_pk_mul_f32 v[14:15], v[0:1], v[14:15]
	v_pk_mul_f32 v[16:17], v[2:3], v[16:17]
	s_nop 0
	v_cvt_pk_bf16_f32 v14, v14, v15
	v_cvt_pk_bf16_f32 v15, v16, v17
	s_nop 0
	global_store_dwordx2 v60, v[14:15], s[14:15] offset:256
.LBB0_1643:
	v_mul_f32_e32 v5, v5, v5
	v_mul_f32_e32 v1, v1, v1
	v_fmac_f32_e32 v5, v4, v4
	v_mul_f32_e32 v4, v7, v7
	v_fmac_f32_e32 v1, v0, v0
	v_mul_f32_e32 v0, v3, v3
	v_fmac_f32_e32 v4, v6, v6
	v_fmac_f32_e32 v0, v2, v2
	v_add_f32_e32 v4, v5, v4
	v_add_f32_e32 v0, v1, v0
	v_add_f32_e32 v0, v4, v0
	ds_bpermute_b32 v1, v40, v0
	v_cmp_eq_u32_e32 vcc, 0, v63
	s_waitcnt lgkmcnt(0)
	v_add_f32_e32 v0, v0, v1
	ds_bpermute_b32 v1, v41, v0
	s_and_saveexec_b64 s[8:9], vcc
	s_cbranch_execz .LBB0_1645
	s_lshl_b64 s[2:3], s[2:3], 2
	s_add_u32 s2, s80, s2
	s_addc_u32 s3, s81, s3
	v_lshlrev_b32_e32 v2, 2, v62
	s_waitcnt lgkmcnt(0)
	v_add_f32_e32 v0, v0, v1
	global_atomic_add_f32 v2, v0, s[2:3]
